# gate sigmoid (proj epilogue) and SiLU (moe_up epilogue) divisions: IEEE div_scale/div_fmas expansion replaced by v_rcp_f32 + one Newton step + v_div_fixup_f32 (f32 throughout)
# speedup vs baseline: 1.0523x; 1.0116x over previous
.LBB0_209:
	s_waitcnt lgkmcnt(1)
	ds_read_b128 v[132:135], v200
	s_waitcnt lgkmcnt(1)
	ds_read_b128 v[128:131], v200 offset:16
	s_and_saveexec_b64 s[28:29], s[48:49]
	s_cbranch_execz .LBB0_211
	s_waitcnt lgkmcnt(1)
	v_mul_f32_e32 v132, 0xbfb8aa3b, v132
	v_mul_f32_e32 v133, 0xbfb8aa3b, v133
	v_exp_f32_e32 v132, v132
	v_exp_f32_e32 v133, v133
	v_mul_f32_e32 v134, 0xbfb8aa3b, v134
	v_mul_f32_e32 v135, 0xbfb8aa3b, v135
	v_exp_f32_e32 v134, v134
	v_pk_add_f32 v[132:133], v[132:133], 1.0 op_sel_hi:[1,0]
	v_exp_f32_e32 v135, v135
	v_mov_b32_e32 v139, v133
	v_rcp_f32_e32 v141, v139
	v_pk_add_f32 v[134:135], v[134:135], 1.0 op_sel_hi:[1,0]
	s_waitcnt lgkmcnt(0)
	v_mul_f32_e32 v128, 0xbfb8aa3b, v128
	v_mul_f32_e32 v129, 0xbfb8aa3b, v129
	v_fma_f32 v143, -v139, v141, 1.0
	v_fmac_f32_e32 v141, v143, v141
	v_div_fixup_f32 v133, v141, v133, 1.0
	v_mov_b32_e32 v139, v132
	v_rcp_f32_e32 v141, v139
	v_exp_f32_e32 v128, v128
	v_exp_f32_e32 v129, v129
	v_mul_f32_e32 v130, 0xbfb8aa3b, v130
	v_fma_f32 v143, -v139, v141, 1.0
	v_fmac_f32_e32 v141, v143, v141
	v_div_fixup_f32 v132, v141, v132, 1.0
	v_mov_b32_e32 v139, v135
	v_rcp_f32_e32 v141, v139
	v_pk_add_f32 v[128:129], v[128:129], 1.0 op_sel_hi:[1,0]
	v_mul_f32_e32 v131, 0xbfb8aa3b, v131
	v_exp_f32_e32 v130, v130
	v_fma_f32 v143, -v139, v141, 1.0
	v_fmac_f32_e32 v141, v143, v141
	v_div_fixup_f32 v135, v141, v135, 1.0
	v_mov_b32_e32 v139, v134
	v_rcp_f32_e32 v141, v139
	v_exp_f32_e32 v131, v131
	v_fma_f32 v143, -v139, v141, 1.0
	v_fmac_f32_e32 v141, v143, v141
	v_div_fixup_f32 v134, v141, v134, 1.0
	v_mov_b32_e32 v139, v129
	v_rcp_f32_e32 v141, v139
	v_pk_add_f32 v[130:131], v[130:131], 1.0 op_sel_hi:[1,0]
	v_fma_f32 v143, -v139, v141, 1.0
	v_fmac_f32_e32 v141, v143, v141
	v_div_fixup_f32 v129, v141, v129, 1.0
	v_mov_b32_e32 v139, v128
	v_rcp_f32_e32 v141, v139
	s_nop 0
	v_fma_f32 v143, -v139, v141, 1.0
	v_fmac_f32_e32 v141, v143, v141
	v_div_fixup_f32 v128, v141, v128, 1.0
	v_mov_b32_e32 v139, v131
	v_rcp_f32_e32 v141, v139
	s_nop 0
	v_fma_f32 v143, -v139, v141, 1.0
	v_fmac_f32_e32 v141, v143, v141
	v_div_fixup_f32 v131, v141, v131, 1.0
	v_mov_b32_e32 v139, v130
	v_rcp_f32_e32 v141, v139
	s_nop 0
	v_fma_f32 v143, -v139, v141, 1.0
	v_fmac_f32_e32 v141, v143, v141
	v_div_fixup_f32 v130, v141, v130, 1.0
.LBB0_211:
	s_or_b64 exec, exec, s[28:29]
	v_mov_b32_e32 v143, v193
	s_waitcnt lgkmcnt(1)
	v_cvt_pk_bf16_f32 v132, v132, v133
	v_cvt_pk_bf16_f32 v133, v134, v135
	s_waitcnt lgkmcnt(0)
	v_cvt_pk_bf16_f32 v134, v128, v129
	v_or_b32_e32 v128, s60, v175
	v_lshl_add_u64 v[162:163], v[162:163], 0, v[142:143]
	v_mad_i64_i32 v[128:129], s[28:29], v160, v128, 0
	v_cvt_pk_bf16_f32 v135, v130, v131
	v_lshl_add_u64 v[128:129], v[128:129], 1, v[162:163]
	global_store_dwordx4 v[128:129], v[132:135], off
	ds_read_b128 v[132:135], v200 offset:8448
	ds_read_b128 v[128:131], v200 offset:8464
	s_and_saveexec_b64 s[28:29], s[48:49]
	s_cbranch_execz .LBB0_213
	s_waitcnt lgkmcnt(1)
	v_mul_f32_e32 v132, 0xbfb8aa3b, v132
	v_mul_f32_e32 v133, 0xbfb8aa3b, v133
	v_exp_f32_e32 v132, v132
	v_exp_f32_e32 v133, v133
	v_mul_f32_e32 v134, 0xbfb8aa3b, v134
	v_mul_f32_e32 v135, 0xbfb8aa3b, v135
	v_exp_f32_e32 v134, v134
	v_pk_add_f32 v[132:133], v[132:133], 1.0 op_sel_hi:[1,0]
	v_exp_f32_e32 v135, v135
	v_mov_b32_e32 v139, v133
	v_rcp_f32_e32 v141, v139
	v_pk_add_f32 v[134:135], v[134:135], 1.0 op_sel_hi:[1,0]
	s_waitcnt lgkmcnt(0)
	v_mul_f32_e32 v128, 0xbfb8aa3b, v128
	v_mul_f32_e32 v129, 0xbfb8aa3b, v129
	v_fma_f32 v143, -v139, v141, 1.0
	v_fmac_f32_e32 v141, v143, v141
	v_div_fixup_f32 v133, v141, v133, 1.0
	v_mov_b32_e32 v139, v132
	v_rcp_f32_e32 v141, v139
	v_exp_f32_e32 v128, v128
	v_exp_f32_e32 v129, v129
	v_mul_f32_e32 v130, 0xbfb8aa3b, v130
	v_fma_f32 v143, -v139, v141, 1.0
	v_fmac_f32_e32 v141, v143, v141
	v_div_fixup_f32 v132, v141, v132, 1.0
	v_mov_b32_e32 v139, v135
	v_rcp_f32_e32 v141, v139
	v_pk_add_f32 v[128:129], v[128:129], 1.0 op_sel_hi:[1,0]
	v_mul_f32_e32 v131, 0xbfb8aa3b, v131
	v_exp_f32_e32 v130, v130
	v_fma_f32 v143, -v139, v141, 1.0
	v_fmac_f32_e32 v141, v143, v141
	v_div_fixup_f32 v135, v141, v135, 1.0
	v_mov_b32_e32 v139, v134
	v_rcp_f32_e32 v141, v139
	v_exp_f32_e32 v131, v131
	v_fma_f32 v143, -v139, v141, 1.0
	v_fmac_f32_e32 v141, v143, v141
	v_div_fixup_f32 v134, v141, v134, 1.0
	v_mov_b32_e32 v139, v129
	v_rcp_f32_e32 v141, v139
	v_pk_add_f32 v[130:131], v[130:131], 1.0 op_sel_hi:[1,0]
	v_fma_f32 v143, -v139, v141, 1.0
	v_fmac_f32_e32 v141, v143, v141
	v_div_fixup_f32 v129, v141, v129, 1.0
	v_mov_b32_e32 v139, v128
	v_rcp_f32_e32 v141, v139
	s_nop 0
	v_fma_f32 v143, -v139, v141, 1.0
	v_fmac_f32_e32 v141, v143, v141
	v_div_fixup_f32 v128, v141, v128, 1.0
	v_mov_b32_e32 v139, v131
	v_rcp_f32_e32 v141, v139
	s_nop 0
	v_fma_f32 v143, -v139, v141, 1.0
	v_fmac_f32_e32 v141, v143, v141
	v_div_fixup_f32 v131, v141, v131, 1.0
	v_mov_b32_e32 v139, v130
	v_rcp_f32_e32 v141, v139
	s_nop 0
	v_fma_f32 v143, -v139, v141, 1.0
	v_fmac_f32_e32 v141, v143, v141
	v_div_fixup_f32 v130, v141, v130, 1.0
.LBB0_213:
	s_or_b64 exec, exec, s[28:29]
	s_waitcnt lgkmcnt(1)
	v_cvt_pk_bf16_f32 v132, v132, v133
	v_cvt_pk_bf16_f32 v133, v134, v135
	s_waitcnt lgkmcnt(0)
	v_cvt_pk_bf16_f32 v134, v128, v129
	v_or_b32_e32 v128, s60, v176
	v_mad_i64_i32 v[128:129], s[28:29], v160, v128, 0
	v_cvt_pk_bf16_f32 v135, v130, v131
	v_lshl_add_u64 v[128:129], v[128:129], 1, v[162:163]
	global_store_dwordx4 v[128:129], v[132:135], off
	ds_read_b128 v[132:135], v200 offset:16896
	ds_read_b128 v[128:131], v200 offset:16912
	s_and_saveexec_b64 s[28:29], s[48:49]
	s_cbranch_execz .LBB0_215
	s_waitcnt lgkmcnt(1)
	v_mul_f32_e32 v132, 0xbfb8aa3b, v132
	v_mul_f32_e32 v133, 0xbfb8aa3b, v133
	v_exp_f32_e32 v132, v132
	v_exp_f32_e32 v133, v133
	v_mul_f32_e32 v134, 0xbfb8aa3b, v134
	v_mul_f32_e32 v135, 0xbfb8aa3b, v135
	v_exp_f32_e32 v134, v134
	v_pk_add_f32 v[132:133], v[132:133], 1.0 op_sel_hi:[1,0]
	v_exp_f32_e32 v135, v135
	v_mov_b32_e32 v139, v133
	v_rcp_f32_e32 v141, v139
	v_pk_add_f32 v[134:135], v[134:135], 1.0 op_sel_hi:[1,0]
	s_waitcnt lgkmcnt(0)
	v_mul_f32_e32 v128, 0xbfb8aa3b, v128
	v_mul_f32_e32 v129, 0xbfb8aa3b, v129
	v_fma_f32 v143, -v139, v141, 1.0
	v_fmac_f32_e32 v141, v143, v141
	v_div_fixup_f32 v133, v141, v133, 1.0
	v_mov_b32_e32 v139, v132
	v_rcp_f32_e32 v141, v139
	v_exp_f32_e32 v128, v128
	v_exp_f32_e32 v129, v129
	v_mul_f32_e32 v130, 0xbfb8aa3b, v130
	v_fma_f32 v143, -v139, v141, 1.0
	v_fmac_f32_e32 v141, v143, v141
	v_div_fixup_f32 v132, v141, v132, 1.0
	v_mov_b32_e32 v139, v135
	v_rcp_f32_e32 v141, v139
	v_pk_add_f32 v[128:129], v[128:129], 1.0 op_sel_hi:[1,0]
	v_mul_f32_e32 v131, 0xbfb8aa3b, v131
	v_exp_f32_e32 v130, v130
	v_fma_f32 v143, -v139, v141, 1.0
	v_fmac_f32_e32 v141, v143, v141
	v_div_fixup_f32 v135, v141, v135, 1.0
	v_mov_b32_e32 v139, v134
	v_rcp_f32_e32 v141, v139
	v_exp_f32_e32 v131, v131
	v_fma_f32 v143, -v139, v141, 1.0
	v_fmac_f32_e32 v141, v143, v141
	v_div_fixup_f32 v134, v141, v134, 1.0
	v_mov_b32_e32 v139, v129
	v_rcp_f32_e32 v141, v139
	v_pk_add_f32 v[130:131], v[130:131], 1.0 op_sel_hi:[1,0]
	v_fma_f32 v143, -v139, v141, 1.0
	v_fmac_f32_e32 v141, v143, v141
	v_div_fixup_f32 v129, v141, v129, 1.0
	v_mov_b32_e32 v139, v128
	v_rcp_f32_e32 v141, v139
	s_nop 0
	v_fma_f32 v143, -v139, v141, 1.0
	v_fmac_f32_e32 v141, v143, v141
	v_div_fixup_f32 v128, v141, v128, 1.0
	v_mov_b32_e32 v139, v131
	v_rcp_f32_e32 v141, v139
	s_nop 0
	v_fma_f32 v143, -v139, v141, 1.0
	v_fmac_f32_e32 v141, v143, v141
	v_div_fixup_f32 v131, v141, v131, 1.0
	v_mov_b32_e32 v139, v130
	v_rcp_f32_e32 v141, v139
	s_nop 0
	v_fma_f32 v143, -v139, v141, 1.0
	v_fmac_f32_e32 v141, v143, v141
	v_div_fixup_f32 v130, v141, v130, 1.0
.LBB0_215:
	s_or_b64 exec, exec, s[28:29]
	s_waitcnt lgkmcnt(1)
	v_cvt_pk_bf16_f32 v132, v132, v133
	v_cvt_pk_bf16_f32 v133, v134, v135
	s_waitcnt lgkmcnt(0)
	v_cvt_pk_bf16_f32 v134, v128, v129
	v_or_b32_e32 v128, s60, v177
	v_mad_i64_i32 v[128:129], s[28:29], v160, v128, 0
	v_cvt_pk_bf16_f32 v135, v130, v131
	v_lshl_add_u64 v[128:129], v[128:129], 1, v[162:163]
	global_store_dwordx4 v[128:129], v[132:135], off
	ds_read_b128 v[132:135], v200 offset:25344
	ds_read_b128 v[128:131], v200 offset:25360
	s_and_saveexec_b64 s[28:29], s[48:49]
	s_cbranch_execz .LBB0_217
	s_waitcnt lgkmcnt(1)
	v_mul_f32_e32 v132, 0xbfb8aa3b, v132
	v_mul_f32_e32 v133, 0xbfb8aa3b, v133
	v_exp_f32_e32 v132, v132
	v_exp_f32_e32 v133, v133
	v_mul_f32_e32 v134, 0xbfb8aa3b, v134
	v_mul_f32_e32 v135, 0xbfb8aa3b, v135
	v_exp_f32_e32 v134, v134
	v_pk_add_f32 v[132:133], v[132:133], 1.0 op_sel_hi:[1,0]
	v_exp_f32_e32 v135, v135
	v_mov_b32_e32 v139, v133
	v_rcp_f32_e32 v141, v139
	v_pk_add_f32 v[134:135], v[134:135], 1.0 op_sel_hi:[1,0]
	s_waitcnt lgkmcnt(0)
	v_mul_f32_e32 v128, 0xbfb8aa3b, v128
	v_mul_f32_e32 v129, 0xbfb8aa3b, v129
	v_fma_f32 v143, -v139, v141, 1.0
	v_fmac_f32_e32 v141, v143, v141
	v_div_fixup_f32 v133, v141, v133, 1.0
	v_mov_b32_e32 v139, v132
	v_rcp_f32_e32 v141, v139
	v_exp_f32_e32 v128, v128
	v_exp_f32_e32 v129, v129
	v_mul_f32_e32 v130, 0xbfb8aa3b, v130
	v_fma_f32 v143, -v139, v141, 1.0
	v_fmac_f32_e32 v141, v143, v141
	v_div_fixup_f32 v132, v141, v132, 1.0
	v_mov_b32_e32 v139, v135
	v_rcp_f32_e32 v141, v139
	v_pk_add_f32 v[128:129], v[128:129], 1.0 op_sel_hi:[1,0]
	v_mul_f32_e32 v131, 0xbfb8aa3b, v131
	v_exp_f32_e32 v130, v130
	v_fma_f32 v143, -v139, v141, 1.0
	v_fmac_f32_e32 v141, v143, v141
	v_div_fixup_f32 v135, v141, v135, 1.0
	v_mov_b32_e32 v139, v134
	v_rcp_f32_e32 v141, v139
	v_exp_f32_e32 v131, v131
	v_fma_f32 v143, -v139, v141, 1.0
	v_fmac_f32_e32 v141, v143, v141
	v_div_fixup_f32 v134, v141, v134, 1.0
	v_mov_b32_e32 v139, v129
	v_rcp_f32_e32 v141, v139
	v_pk_add_f32 v[130:131], v[130:131], 1.0 op_sel_hi:[1,0]
	v_fma_f32 v143, -v139, v141, 1.0
	v_fmac_f32_e32 v141, v143, v141
	v_div_fixup_f32 v129, v141, v129, 1.0
	v_mov_b32_e32 v139, v128
	v_rcp_f32_e32 v141, v139
	s_nop 0
	v_fma_f32 v143, -v139, v141, 1.0
	v_fmac_f32_e32 v141, v143, v141
	v_div_fixup_f32 v128, v141, v128, 1.0
	v_mov_b32_e32 v139, v131
	v_rcp_f32_e32 v141, v139
	s_nop 0
	v_fma_f32 v143, -v139, v141, 1.0
	v_fmac_f32_e32 v141, v143, v141
	v_div_fixup_f32 v131, v141, v131, 1.0
	v_mov_b32_e32 v139, v130
	v_rcp_f32_e32 v141, v139
	s_nop 0
	v_fma_f32 v143, -v139, v141, 1.0
	v_fmac_f32_e32 v141, v143, v141
	v_div_fixup_f32 v130, v141, v130, 1.0
.LBB0_217:
	s_or_b64 exec, exec, s[28:29]
	s_waitcnt lgkmcnt(1)
	v_cvt_pk_bf16_f32 v132, v132, v133
	v_cvt_pk_bf16_f32 v133, v134, v135
	s_waitcnt lgkmcnt(0)
	v_cvt_pk_bf16_f32 v134, v128, v129
	v_or_b32_e32 v128, s60, v178
	v_mad_i64_i32 v[128:129], s[28:29], v160, v128, 0
	v_cvt_pk_bf16_f32 v135, v130, v131
	v_lshl_add_u64 v[128:129], v[128:129], 1, v[162:163]
	global_store_dwordx4 v[128:129], v[132:135], off
	ds_read_b128 v[132:135], v200 offset:33792
	ds_read_b128 v[128:131], v200 offset:33808
	s_and_saveexec_b64 s[28:29], s[48:49]
	s_cbranch_execz .LBB0_219
	s_waitcnt lgkmcnt(1)
	v_mul_f32_e32 v132, 0xbfb8aa3b, v132
	v_mul_f32_e32 v133, 0xbfb8aa3b, v133
	v_exp_f32_e32 v132, v132
	v_exp_f32_e32 v133, v133
	v_mul_f32_e32 v134, 0xbfb8aa3b, v134
	v_mul_f32_e32 v135, 0xbfb8aa3b, v135
	v_exp_f32_e32 v134, v134
	v_pk_add_f32 v[132:133], v[132:133], 1.0 op_sel_hi:[1,0]
	v_exp_f32_e32 v135, v135
	v_mov_b32_e32 v139, v133
	v_rcp_f32_e32 v141, v139
	v_pk_add_f32 v[134:135], v[134:135], 1.0 op_sel_hi:[1,0]
	s_waitcnt lgkmcnt(0)
	v_mul_f32_e32 v128, 0xbfb8aa3b, v128
	v_mul_f32_e32 v129, 0xbfb8aa3b, v129
	v_fma_f32 v143, -v139, v141, 1.0
	v_fmac_f32_e32 v141, v143, v141
	v_div_fixup_f32 v133, v141, v133, 1.0
	v_mov_b32_e32 v139, v132
	v_rcp_f32_e32 v141, v139
	v_exp_f32_e32 v128, v128
	v_exp_f32_e32 v129, v129
	v_mul_f32_e32 v130, 0xbfb8aa3b, v130
	v_fma_f32 v143, -v139, v141, 1.0
	v_fmac_f32_e32 v141, v143, v141
	v_div_fixup_f32 v132, v141, v132, 1.0
	v_mov_b32_e32 v139, v135
	v_rcp_f32_e32 v141, v139
	v_pk_add_f32 v[128:129], v[128:129], 1.0 op_sel_hi:[1,0]
	v_mul_f32_e32 v131, 0xbfb8aa3b, v131
	v_exp_f32_e32 v130, v130
	v_fma_f32 v143, -v139, v141, 1.0
	v_fmac_f32_e32 v141, v143, v141
	v_div_fixup_f32 v135, v141, v135, 1.0
	v_mov_b32_e32 v139, v134
	v_rcp_f32_e32 v141, v139
	v_exp_f32_e32 v131, v131
	v_fma_f32 v143, -v139, v141, 1.0
	v_fmac_f32_e32 v141, v143, v141
	v_div_fixup_f32 v134, v141, v134, 1.0
	v_mov_b32_e32 v139, v129
	v_rcp_f32_e32 v141, v139
	v_pk_add_f32 v[130:131], v[130:131], 1.0 op_sel_hi:[1,0]
	v_fma_f32 v143, -v139, v141, 1.0
	v_fmac_f32_e32 v141, v143, v141
	v_div_fixup_f32 v129, v141, v129, 1.0
	v_mov_b32_e32 v139, v128
	v_rcp_f32_e32 v141, v139
	s_nop 0
	v_fma_f32 v143, -v139, v141, 1.0
	v_fmac_f32_e32 v141, v143, v141
	v_div_fixup_f32 v128, v141, v128, 1.0
	v_mov_b32_e32 v139, v131
	v_rcp_f32_e32 v141, v139
	s_nop 0
	v_fma_f32 v143, -v139, v141, 1.0
	v_fmac_f32_e32 v141, v143, v141
	v_div_fixup_f32 v131, v141, v131, 1.0
	v_mov_b32_e32 v139, v130
	v_rcp_f32_e32 v141, v139
	s_nop 0
	v_fma_f32 v143, -v139, v141, 1.0
	v_fmac_f32_e32 v141, v143, v141
	v_div_fixup_f32 v130, v141, v130, 1.0
.LBB0_219:
	s_or_b64 exec, exec, s[28:29]
	s_waitcnt lgkmcnt(1)
	v_cvt_pk_bf16_f32 v132, v132, v133
	v_cvt_pk_bf16_f32 v133, v134, v135
	s_waitcnt lgkmcnt(0)
	v_cvt_pk_bf16_f32 v134, v128, v129
	v_or_b32_e32 v128, s60, v179
	v_mad_i64_i32 v[128:129], s[28:29], v160, v128, 0
	v_cvt_pk_bf16_f32 v135, v130, v131
	v_lshl_add_u64 v[128:129], v[128:129], 1, v[162:163]
	global_store_dwordx4 v[128:129], v[132:135], off
	ds_read_b128 v[132:135], v200 offset:42240
	ds_read_b128 v[128:131], v200 offset:42256
	s_and_saveexec_b64 s[28:29], s[48:49]
	s_cbranch_execz .LBB0_221
	s_waitcnt lgkmcnt(1)
	v_mul_f32_e32 v132, 0xbfb8aa3b, v132
	v_mul_f32_e32 v133, 0xbfb8aa3b, v133
	v_exp_f32_e32 v132, v132
	v_exp_f32_e32 v133, v133
	v_mul_f32_e32 v134, 0xbfb8aa3b, v134
	v_mul_f32_e32 v135, 0xbfb8aa3b, v135
	v_exp_f32_e32 v134, v134
	v_pk_add_f32 v[132:133], v[132:133], 1.0 op_sel_hi:[1,0]
	v_exp_f32_e32 v135, v135
	v_mov_b32_e32 v139, v133
	v_rcp_f32_e32 v141, v139
	v_pk_add_f32 v[134:135], v[134:135], 1.0 op_sel_hi:[1,0]
	s_waitcnt lgkmcnt(0)
	v_mul_f32_e32 v128, 0xbfb8aa3b, v128
	v_mul_f32_e32 v129, 0xbfb8aa3b, v129
	v_fma_f32 v143, -v139, v141, 1.0
	v_fmac_f32_e32 v141, v143, v141
	v_div_fixup_f32 v133, v141, v133, 1.0
	v_mov_b32_e32 v139, v132
	v_rcp_f32_e32 v141, v139
	v_exp_f32_e32 v128, v128
	v_exp_f32_e32 v129, v129
	v_mul_f32_e32 v130, 0xbfb8aa3b, v130
	v_fma_f32 v143, -v139, v141, 1.0
	v_fmac_f32_e32 v141, v143, v141
	v_div_fixup_f32 v132, v141, v132, 1.0
	v_mov_b32_e32 v139, v135
	v_rcp_f32_e32 v141, v139
	v_pk_add_f32 v[128:129], v[128:129], 1.0 op_sel_hi:[1,0]
	v_mul_f32_e32 v131, 0xbfb8aa3b, v131
	v_exp_f32_e32 v130, v130
	v_fma_f32 v143, -v139, v141, 1.0
	v_fmac_f32_e32 v141, v143, v141
	v_div_fixup_f32 v135, v141, v135, 1.0
	v_mov_b32_e32 v139, v134
	v_rcp_f32_e32 v141, v139
	v_exp_f32_e32 v131, v131
	v_fma_f32 v143, -v139, v141, 1.0
	v_fmac_f32_e32 v141, v143, v141
	v_div_fixup_f32 v134, v141, v134, 1.0
	v_mov_b32_e32 v139, v129
	v_rcp_f32_e32 v141, v139
	v_pk_add_f32 v[130:131], v[130:131], 1.0 op_sel_hi:[1,0]
	v_fma_f32 v143, -v139, v141, 1.0
	v_fmac_f32_e32 v141, v143, v141
	v_div_fixup_f32 v129, v141, v129, 1.0
	v_mov_b32_e32 v139, v128
	v_rcp_f32_e32 v141, v139
	s_nop 0
	v_fma_f32 v143, -v139, v141, 1.0
	v_fmac_f32_e32 v141, v143, v141
	v_div_fixup_f32 v128, v141, v128, 1.0
	v_mov_b32_e32 v139, v131
	v_rcp_f32_e32 v141, v139
	s_nop 0
	v_fma_f32 v143, -v139, v141, 1.0
	v_fmac_f32_e32 v141, v143, v141
	v_div_fixup_f32 v131, v141, v131, 1.0
	v_mov_b32_e32 v139, v130
	v_rcp_f32_e32 v141, v139
	s_nop 0
	v_fma_f32 v143, -v139, v141, 1.0
	v_fmac_f32_e32 v141, v143, v141
	v_div_fixup_f32 v130, v141, v130, 1.0
.LBB0_221:
	s_or_b64 exec, exec, s[28:29]
	s_waitcnt lgkmcnt(1)
	v_cvt_pk_bf16_f32 v132, v132, v133
	v_cvt_pk_bf16_f32 v133, v134, v135
	s_waitcnt lgkmcnt(0)
	v_cvt_pk_bf16_f32 v134, v128, v129
	v_or_b32_e32 v128, s60, v180
	v_mad_i64_i32 v[128:129], s[28:29], v160, v128, 0
	v_cvt_pk_bf16_f32 v135, v130, v131
	v_lshl_add_u64 v[128:129], v[128:129], 1, v[162:163]
	global_store_dwordx4 v[128:129], v[132:135], off
	ds_read_b128 v[132:135], v200 offset:50688
	ds_read_b128 v[128:131], v200 offset:50704
	s_and_saveexec_b64 s[28:29], s[48:49]
	s_cbranch_execz .LBB0_223
	s_waitcnt lgkmcnt(1)
	v_mul_f32_e32 v132, 0xbfb8aa3b, v132
	v_mul_f32_e32 v133, 0xbfb8aa3b, v133
	v_exp_f32_e32 v132, v132
	v_exp_f32_e32 v133, v133
	v_mul_f32_e32 v134, 0xbfb8aa3b, v134
	v_mul_f32_e32 v135, 0xbfb8aa3b, v135
	v_exp_f32_e32 v134, v134
	v_pk_add_f32 v[132:133], v[132:133], 1.0 op_sel_hi:[1,0]
	v_exp_f32_e32 v135, v135
	v_mov_b32_e32 v139, v133
	v_rcp_f32_e32 v141, v139
	v_pk_add_f32 v[134:135], v[134:135], 1.0 op_sel_hi:[1,0]
	s_waitcnt lgkmcnt(0)
	v_mul_f32_e32 v128, 0xbfb8aa3b, v128
	v_mul_f32_e32 v129, 0xbfb8aa3b, v129
	v_fma_f32 v143, -v139, v141, 1.0
	v_fmac_f32_e32 v141, v143, v141
	v_div_fixup_f32 v133, v141, v133, 1.0
	v_mov_b32_e32 v139, v132
	v_rcp_f32_e32 v141, v139
	v_exp_f32_e32 v128, v128
	v_exp_f32_e32 v129, v129
	v_mul_f32_e32 v130, 0xbfb8aa3b, v130
	v_fma_f32 v143, -v139, v141, 1.0
	v_fmac_f32_e32 v141, v143, v141
	v_div_fixup_f32 v132, v141, v132, 1.0
	v_mov_b32_e32 v139, v135
	v_rcp_f32_e32 v141, v139
	v_pk_add_f32 v[128:129], v[128:129], 1.0 op_sel_hi:[1,0]
	v_mul_f32_e32 v131, 0xbfb8aa3b, v131
	v_exp_f32_e32 v130, v130
	v_fma_f32 v143, -v139, v141, 1.0
	v_fmac_f32_e32 v141, v143, v141
	v_div_fixup_f32 v135, v141, v135, 1.0
	v_mov_b32_e32 v139, v134
	v_rcp_f32_e32 v141, v139
	v_exp_f32_e32 v131, v131
	v_fma_f32 v143, -v139, v141, 1.0
	v_fmac_f32_e32 v141, v143, v141
	v_div_fixup_f32 v134, v141, v134, 1.0
	v_mov_b32_e32 v139, v129
	v_rcp_f32_e32 v141, v139
	v_pk_add_f32 v[130:131], v[130:131], 1.0 op_sel_hi:[1,0]
	v_fma_f32 v143, -v139, v141, 1.0
	v_fmac_f32_e32 v141, v143, v141
	v_div_fixup_f32 v129, v141, v129, 1.0
	v_mov_b32_e32 v139, v128
	v_rcp_f32_e32 v141, v139
	s_nop 0
	v_fma_f32 v143, -v139, v141, 1.0
	v_fmac_f32_e32 v141, v143, v141
	v_div_fixup_f32 v128, v141, v128, 1.0
	v_mov_b32_e32 v139, v131
	v_rcp_f32_e32 v141, v139
	s_nop 0
	v_fma_f32 v143, -v139, v141, 1.0
	v_fmac_f32_e32 v141, v143, v141
	v_div_fixup_f32 v131, v141, v131, 1.0
	v_mov_b32_e32 v139, v130
	v_rcp_f32_e32 v141, v139
	s_nop 0
	v_fma_f32 v143, -v139, v141, 1.0
	v_fmac_f32_e32 v141, v143, v141
	v_div_fixup_f32 v130, v141, v130, 1.0
.LBB0_223:
	s_or_b64 exec, exec, s[28:29]
	s_waitcnt lgkmcnt(1)
	v_cvt_pk_bf16_f32 v132, v132, v133
	v_cvt_pk_bf16_f32 v133, v134, v135
	s_waitcnt lgkmcnt(0)
	v_cvt_pk_bf16_f32 v134, v128, v129
	v_or_b32_e32 v128, s60, v181
	v_mad_i64_i32 v[128:129], s[28:29], v160, v128, 0
	v_cvt_pk_bf16_f32 v135, v130, v131
	v_lshl_add_u64 v[128:129], v[128:129], 1, v[162:163]
	global_store_dwordx4 v[128:129], v[132:135], off
	ds_read_b128 v[128:131], v200 offset:59136
	ds_read_b128 v[132:135], v200 offset:59152
	s_and_saveexec_b64 s[28:29], s[48:49]
	s_cbranch_execz .LBB0_225
	s_waitcnt lgkmcnt(1)
	v_mul_f32_e32 v128, 0xbfb8aa3b, v128
	v_mul_f32_e32 v129, 0xbfb8aa3b, v129
	v_exp_f32_e32 v128, v128
	v_exp_f32_e32 v129, v129
	v_mul_f32_e32 v130, 0xbfb8aa3b, v130
	v_mul_f32_e32 v131, 0xbfb8aa3b, v131
	v_exp_f32_e32 v130, v130
	v_pk_add_f32 v[128:129], v[128:129], 1.0 op_sel_hi:[1,0]
	v_exp_f32_e32 v131, v131
	v_mov_b32_e32 v139, v129
	v_rcp_f32_e32 v141, v139
	v_pk_add_f32 v[130:131], v[130:131], 1.0 op_sel_hi:[1,0]
	s_waitcnt lgkmcnt(0)
	v_mul_f32_e32 v132, 0xbfb8aa3b, v132
	v_mul_f32_e32 v133, 0xbfb8aa3b, v133
	v_fma_f32 v143, -v139, v141, 1.0
	v_fmac_f32_e32 v141, v143, v141
	v_div_fixup_f32 v129, v141, v129, 1.0
	v_mov_b32_e32 v139, v128
	v_rcp_f32_e32 v141, v139
	v_exp_f32_e32 v132, v132
	v_exp_f32_e32 v133, v133
	v_mul_f32_e32 v134, 0xbfb8aa3b, v134
	v_fma_f32 v143, -v139, v141, 1.0
	v_fmac_f32_e32 v141, v143, v141
	v_div_fixup_f32 v128, v141, v128, 1.0
	v_mov_b32_e32 v139, v131
	v_rcp_f32_e32 v141, v139
	v_pk_add_f32 v[132:133], v[132:133], 1.0 op_sel_hi:[1,0]
	v_mul_f32_e32 v135, 0xbfb8aa3b, v135
	v_exp_f32_e32 v134, v134
	v_fma_f32 v143, -v139, v141, 1.0
	v_fmac_f32_e32 v141, v143, v141
	v_div_fixup_f32 v131, v141, v131, 1.0
	v_mov_b32_e32 v139, v130
	v_rcp_f32_e32 v141, v139
	v_exp_f32_e32 v135, v135
	v_fma_f32 v143, -v139, v141, 1.0
	v_fmac_f32_e32 v141, v143, v141
	v_div_fixup_f32 v130, v141, v130, 1.0
	v_mov_b32_e32 v139, v133
	v_rcp_f32_e32 v141, v139
	v_pk_add_f32 v[134:135], v[134:135], 1.0 op_sel_hi:[1,0]
	v_fma_f32 v143, -v139, v141, 1.0
	v_fmac_f32_e32 v141, v143, v141
	v_div_fixup_f32 v133, v141, v133, 1.0
	v_mov_b32_e32 v139, v132
	v_rcp_f32_e32 v141, v139
	s_nop 0
	v_fma_f32 v143, -v139, v141, 1.0
	v_fmac_f32_e32 v141, v143, v141
	v_div_fixup_f32 v132, v141, v132, 1.0
	v_mov_b32_e32 v139, v135
	v_rcp_f32_e32 v141, v139
	s_nop 0
	v_fma_f32 v143, -v139, v141, 1.0
	v_fmac_f32_e32 v141, v143, v141
	v_div_fixup_f32 v135, v141, v135, 1.0
	v_mov_b32_e32 v139, v134
	v_rcp_f32_e32 v141, v139
	s_nop 0
	v_fma_f32 v143, -v139, v141, 1.0
	v_fmac_f32_e32 v141, v143, v141
	v_div_fixup_f32 v134, v141, v134, 1.0

.LBB0_738:
	s_or_b64 exec, exec, s[46:47]
	s_lshl_b32 s46, s48, 7
	s_or_b32 s46, s46, s60
	v_or_b32_e32 v146, s46, v138
	v_cmp_lt_i32_e32 vcc, v146, v140
	s_waitcnt lgkmcnt(0)
	s_barrier
	s_and_saveexec_b64 s[48:49], vcc
	s_cbranch_execz .LBB0_740
	v_ashrrev_i32_e32 v147, 31, v146
	v_lshl_add_u64 v[128:129], v[146:147], 2, v[142:143]
	global_load_dword v148, v[128:129], off
	ds_read_b128 v[132:135], v166
	ds_read_b128 v[128:131], v166 offset:16
	ds_read_b128 v[150:153], v166 offset:256
	s_waitcnt lgkmcnt(2)
	v_mul_f32_e32 v147, 0xbfb8aa3b, v132
	v_exp_f32_e32 v154, v147
	v_mul_f32_e32 v147, 0xbfb8aa3b, v133
	v_exp_f32_e32 v155, v147
	s_nop 0
	v_pk_add_f32 v[154:155], v[154:155], 1.0 op_sel_hi:[1,0]
	s_nop 0
	v_mov_b32_e32 v147, v155
	v_rcp_f32_e32 v149, v147
	s_nop 0
	v_fma_f32 v167, -v147, v149, 1.0
	v_fmac_f32_e32 v149, v167, v149
	v_mul_f32_e32 v168, v133, v149
	v_div_fixup_f32 v133, v168, v155, v133
	v_mov_b32_e32 v147, v154
	v_rcp_f32_e32 v149, v147
	s_nop 0
	v_fma_f32 v155, -v147, v149, 1.0
	v_fmac_f32_e32 v149, v155, v149
	v_mul_f32_e32 v167, v132, v149
	v_div_fixup_f32 v132, v167, v154, v132
	s_waitcnt lgkmcnt(0)
	v_pk_mul_f32 v[132:133], v[150:151], v[132:133]
	s_waitcnt vmcnt(0)
	v_pk_mul_f32 v[150:151], v[148:149], v[132:133] op_sel_hi:[0,1]
	v_mul_f32_e32 v132, 0xbfb8aa3b, v134
	v_mul_f32_e32 v133, 0xbfb8aa3b, v135
	v_exp_f32_e32 v132, v132
	v_exp_f32_e32 v133, v133
	s_nop 0
	v_pk_add_f32 v[132:133], v[132:133], 1.0 op_sel_hi:[1,0]
	s_nop 0
	v_mov_b32_e32 v147, v133
	v_rcp_f32_e32 v149, v147
	s_nop 0
	v_fma_f32 v154, -v147, v149, 1.0
	v_fmac_f32_e32 v149, v154, v149
	v_mul_f32_e32 v155, v135, v149
	v_div_fixup_f32 v133, v155, v133, v135
	v_mov_b32_e32 v135, v132
	v_rcp_f32_e32 v147, v135
	s_nop 0
	v_fma_f32 v149, -v135, v147, 1.0
	v_fmac_f32_e32 v147, v149, v147
	v_mul_f32_e32 v154, v134, v147
	v_div_fixup_f32 v132, v154, v132, v134
	v_pk_mul_f32 v[132:133], v[152:153], v[132:133]
	v_mul_f32_e32 v147, 0xbfb8aa3b, v129
	v_pk_mul_f32 v[152:153], v[148:149], v[132:133] op_sel_hi:[0,1]
	v_mul_f32_e32 v132, 0xbfb8aa3b, v128
	v_exp_f32_e32 v154, v132
	v_exp_f32_e32 v155, v147
	ds_read_b128 v[132:135], v166 offset:272
	v_pk_add_f32 v[154:155], v[154:155], 1.0 op_sel_hi:[1,0]
	s_nop 0
	v_mov_b32_e32 v147, v155
	v_rcp_f32_e32 v149, v147
	s_nop 0
	v_fma_f32 v167, -v147, v149, 1.0
	v_fmac_f32_e32 v149, v167, v149
	v_mul_f32_e32 v168, v129, v149
	v_div_fixup_f32 v129, v168, v155, v129
	v_mov_b32_e32 v147, v154
	v_rcp_f32_e32 v149, v147
	s_nop 0
	v_fma_f32 v155, -v147, v149, 1.0
	v_fmac_f32_e32 v149, v155, v149
	v_mul_f32_e32 v167, v128, v149
	v_div_fixup_f32 v128, v167, v154, v128
	s_waitcnt lgkmcnt(0)
	v_pk_mul_f32 v[128:129], v[132:133], v[128:129]
	s_nop 0
	v_pk_mul_f32 v[132:133], v[148:149], v[128:129] op_sel_hi:[0,1]
	v_mul_f32_e32 v128, 0xbfb8aa3b, v130
	v_mul_f32_e32 v129, 0xbfb8aa3b, v131
	v_exp_f32_e32 v128, v128
	v_exp_f32_e32 v129, v129
	s_nop 0
	v_pk_add_f32 v[128:129], v[128:129], 1.0 op_sel_hi:[1,0]
	s_nop 0
	v_mov_b32_e32 v147, v129
	v_rcp_f32_e32 v149, v147
	s_nop 0
	v_fma_f32 v154, -v147, v149, 1.0
	v_fmac_f32_e32 v149, v154, v149
	v_mul_f32_e32 v155, v131, v149
	v_div_fixup_f32 v129, v155, v129, v131
	v_mov_b32_e32 v131, v128
	v_rcp_f32_e32 v147, v131
	s_nop 0
	v_fma_f32 v149, -v131, v147, 1.0
	v_fmac_f32_e32 v147, v149, v147
	v_mul_f32_e32 v154, v130, v147
	v_div_fixup_f32 v128, v154, v128, v130
	v_cvt_pk_bf16_f32 v130, v132, v133
	v_add_u32_e32 v132, v146, v141
	v_pk_mul_f32 v[128:129], v[134:135], v[128:129]
	v_ashrrev_i32_e32 v133, 31, v132
	v_pk_mul_f32 v[134:135], v[148:149], v[128:129] op_sel_hi:[0,1]
	v_lshlrev_b64 v[132:133], 10, v[132:133]
	v_cvt_pk_bf16_f32 v128, v150, v151
	v_cvt_pk_bf16_f32 v129, v152, v153
	v_cvt_pk_bf16_f32 v131, v134, v135
	v_lshl_add_u64 v[132:133], v[144:145], 0, v[132:133]
	global_store_dwordx4 v[132:133], v[128:131], off
.LBB0_740:
	s_or_b64 exec, exec, s[48:49]
	v_or_b32_e32 v147, s46, v159
	v_cmp_lt_i32_e32 vcc, v147, v140
	s_and_saveexec_b64 s[48:49], vcc
	s_cbranch_execz .LBB0_742
	s_ashr_i32 s47, s46, 31
	v_lshl_add_u64 v[128:129], s[46:47], 0, v[138:139]
	v_lshl_add_u64 v[128:129], v[128:129], 2, v[142:143]
	global_load_dword v146, v[128:129], off offset:128
	ds_read_b128 v[132:135], v166 offset:16896
	ds_read_b128 v[128:131], v166 offset:16912
	s_waitcnt lgkmcnt(1)
	v_mul_f32_e32 v148, 0xbfb8aa3b, v132
	v_mul_f32_e32 v153, 0xbfb8aa3b, v133
	v_exp_f32_e32 v152, v148
	v_exp_f32_e32 v153, v153
	ds_read_b128 v[148:151], v166 offset:17152
	v_pk_add_f32 v[152:153], v[152:153], 1.0 op_sel_hi:[1,0]
	s_nop 0
	v_mov_b32_e32 v154, v153
	v_rcp_f32_e32 v155, v154
	s_nop 0
	v_fma_f32 v167, -v154, v155, 1.0
	v_fmac_f32_e32 v155, v167, v155
	v_mul_f32_e32 v168, v133, v155
	v_div_fixup_f32 v133, v168, v153, v133
	v_mov_b32_e32 v153, v152
	v_rcp_f32_e32 v154, v153
	s_nop 0
	v_fma_f32 v155, -v153, v154, 1.0
	v_fmac_f32_e32 v154, v155, v154
	v_mul_f32_e32 v167, v132, v154
	v_div_fixup_f32 v132, v167, v152, v132
	s_waitcnt lgkmcnt(0)
	v_pk_mul_f32 v[132:133], v[148:149], v[132:133]
	s_waitcnt vmcnt(0)
	v_pk_mul_f32 v[148:149], v[146:147], v[132:133] op_sel_hi:[0,1]
	v_mul_f32_e32 v132, 0xbfb8aa3b, v134
	v_mul_f32_e32 v133, 0xbfb8aa3b, v135
	v_exp_f32_e32 v132, v132
	v_exp_f32_e32 v133, v133
	s_nop 0
	v_pk_add_f32 v[132:133], v[132:133], 1.0 op_sel_hi:[1,0]
	s_nop 0
	v_mov_b32_e32 v152, v133
	v_rcp_f32_e32 v153, v152
	s_nop 0
	v_fma_f32 v154, -v152, v153, 1.0
	v_fmac_f32_e32 v153, v154, v153
	v_mul_f32_e32 v155, v135, v153
	v_div_fixup_f32 v133, v155, v133, v135
	v_mov_b32_e32 v135, v132
	v_rcp_f32_e32 v152, v135
	s_nop 0
	v_fma_f32 v153, -v135, v152, 1.0
	v_fmac_f32_e32 v152, v153, v152
	v_mul_f32_e32 v154, v134, v152
	v_div_fixup_f32 v132, v154, v132, v134
	v_pk_mul_f32 v[132:133], v[150:151], v[132:133]
	v_mul_f32_e32 v153, 0xbfb8aa3b, v129
	v_pk_mul_f32 v[150:151], v[146:147], v[132:133] op_sel_hi:[0,1]
	v_mul_f32_e32 v132, 0xbfb8aa3b, v128
	v_exp_f32_e32 v152, v132
	v_exp_f32_e32 v153, v153
	ds_read_b128 v[132:135], v166 offset:17168
	v_pk_add_f32 v[152:153], v[152:153], 1.0 op_sel_hi:[1,0]
	s_nop 0
	v_mov_b32_e32 v154, v153
	v_rcp_f32_e32 v155, v154
	s_nop 0
	v_fma_f32 v167, -v154, v155, 1.0
	v_fmac_f32_e32 v155, v167, v155
	v_mul_f32_e32 v168, v129, v155
	v_div_fixup_f32 v129, v168, v153, v129
	v_mov_b32_e32 v153, v152
	v_rcp_f32_e32 v154, v153
	s_nop 0
	v_fma_f32 v155, -v153, v154, 1.0
	v_fmac_f32_e32 v154, v155, v154
	v_mul_f32_e32 v167, v128, v154
	v_div_fixup_f32 v128, v167, v152, v128
	s_waitcnt lgkmcnt(0)
	v_pk_mul_f32 v[128:129], v[132:133], v[128:129]
	s_nop 0
	v_pk_mul_f32 v[132:133], v[146:147], v[128:129] op_sel_hi:[0,1]
	v_mul_f32_e32 v128, 0xbfb8aa3b, v130
	v_mul_f32_e32 v129, 0xbfb8aa3b, v131
	v_exp_f32_e32 v128, v128
	v_exp_f32_e32 v129, v129
	s_nop 0
	v_pk_add_f32 v[128:129], v[128:129], 1.0 op_sel_hi:[1,0]
	s_nop 0
	v_mov_b32_e32 v152, v129
	v_rcp_f32_e32 v153, v152
	s_nop 0
	v_fma_f32 v154, -v152, v153, 1.0
	v_fmac_f32_e32 v153, v154, v153
	v_mul_f32_e32 v155, v131, v153
	v_div_fixup_f32 v129, v155, v129, v131
	v_mov_b32_e32 v131, v128
	v_rcp_f32_e32 v152, v131
	s_nop 0
	v_fma_f32 v153, -v131, v152, 1.0
	v_fmac_f32_e32 v152, v153, v152
	v_mul_f32_e32 v154, v130, v152
	v_div_fixup_f32 v128, v154, v128, v130
	v_cvt_pk_bf16_f32 v130, v132, v133
	v_add_u32_e32 v132, v147, v141
	v_pk_mul_f32 v[128:129], v[134:135], v[128:129]
	v_ashrrev_i32_e32 v133, 31, v132
	v_pk_mul_f32 v[134:135], v[146:147], v[128:129] op_sel_hi:[0,1]
	v_lshlrev_b64 v[132:133], 10, v[132:133]
	v_cvt_pk_bf16_f32 v128, v148, v149
	v_cvt_pk_bf16_f32 v129, v150, v151
	v_cvt_pk_bf16_f32 v131, v134, v135
	v_lshl_add_u64 v[132:133], v[144:145], 0, v[132:133]
	global_store_dwordx4 v[132:133], v[128:131], off
.LBB0_742:
	s_or_b64 exec, exec, s[48:49]
	v_or_b32_e32 v147, s46, v160
	v_cmp_lt_i32_e32 vcc, v147, v140
	s_and_saveexec_b64 s[48:49], vcc
	s_cbranch_execz .LBB0_744
	s_ashr_i32 s47, s46, 31
	v_lshl_add_u64 v[128:129], s[46:47], 0, v[138:139]
	v_lshl_add_u64 v[128:129], v[128:129], 2, v[142:143]
	global_load_dword v146, v[128:129], off offset:256
	ds_read_b128 v[132:135], v166 offset:33792
	ds_read_b128 v[128:131], v166 offset:33808
	s_waitcnt lgkmcnt(1)
	v_mul_f32_e32 v148, 0xbfb8aa3b, v132
	v_mul_f32_e32 v153, 0xbfb8aa3b, v133
	v_exp_f32_e32 v152, v148
	v_exp_f32_e32 v153, v153
	ds_read_b128 v[148:151], v166 offset:34048
	v_pk_add_f32 v[152:153], v[152:153], 1.0 op_sel_hi:[1,0]
	s_nop 0
	v_mov_b32_e32 v154, v153
	v_rcp_f32_e32 v155, v154
	s_nop 0
	v_fma_f32 v167, -v154, v155, 1.0
	v_fmac_f32_e32 v155, v167, v155
	v_mul_f32_e32 v168, v133, v155
	v_div_fixup_f32 v133, v168, v153, v133
	v_mov_b32_e32 v153, v152
	v_rcp_f32_e32 v154, v153
	s_nop 0
	v_fma_f32 v155, -v153, v154, 1.0
	v_fmac_f32_e32 v154, v155, v154
	v_mul_f32_e32 v167, v132, v154
	v_div_fixup_f32 v132, v167, v152, v132
	s_waitcnt lgkmcnt(0)
	v_pk_mul_f32 v[132:133], v[148:149], v[132:133]
	s_waitcnt vmcnt(0)
	v_pk_mul_f32 v[148:149], v[146:147], v[132:133] op_sel_hi:[0,1]
	v_mul_f32_e32 v132, 0xbfb8aa3b, v134
	v_mul_f32_e32 v133, 0xbfb8aa3b, v135
	v_exp_f32_e32 v132, v132
	v_exp_f32_e32 v133, v133
	s_nop 0
	v_pk_add_f32 v[132:133], v[132:133], 1.0 op_sel_hi:[1,0]
	s_nop 0
	v_mov_b32_e32 v152, v133
	v_rcp_f32_e32 v153, v152
	s_nop 0
	v_fma_f32 v154, -v152, v153, 1.0
	v_fmac_f32_e32 v153, v154, v153
	v_mul_f32_e32 v155, v135, v153
	v_div_fixup_f32 v133, v155, v133, v135
	v_mov_b32_e32 v135, v132
	v_rcp_f32_e32 v152, v135
	s_nop 0
	v_fma_f32 v153, -v135, v152, 1.0
	v_fmac_f32_e32 v152, v153, v152
	v_mul_f32_e32 v154, v134, v152
	v_div_fixup_f32 v132, v154, v132, v134
	v_pk_mul_f32 v[132:133], v[150:151], v[132:133]
	v_mul_f32_e32 v153, 0xbfb8aa3b, v129
	v_pk_mul_f32 v[150:151], v[146:147], v[132:133] op_sel_hi:[0,1]
	v_mul_f32_e32 v132, 0xbfb8aa3b, v128
	v_exp_f32_e32 v152, v132
	v_exp_f32_e32 v153, v153
	ds_read_b128 v[132:135], v166 offset:34064
	v_pk_add_f32 v[152:153], v[152:153], 1.0 op_sel_hi:[1,0]
	s_nop 0
	v_mov_b32_e32 v154, v153
	v_rcp_f32_e32 v155, v154
	s_nop 0
	v_fma_f32 v167, -v154, v155, 1.0
	v_fmac_f32_e32 v155, v167, v155
	v_mul_f32_e32 v168, v129, v155
	v_div_fixup_f32 v129, v168, v153, v129
	v_mov_b32_e32 v153, v152
	v_rcp_f32_e32 v154, v153
	s_nop 0
	v_fma_f32 v155, -v153, v154, 1.0
	v_fmac_f32_e32 v154, v155, v154
	v_mul_f32_e32 v167, v128, v154
	v_div_fixup_f32 v128, v167, v152, v128
	s_waitcnt lgkmcnt(0)
	v_pk_mul_f32 v[128:129], v[132:133], v[128:129]
	s_nop 0
	v_pk_mul_f32 v[132:133], v[146:147], v[128:129] op_sel_hi:[0,1]
	v_mul_f32_e32 v128, 0xbfb8aa3b, v130
	v_mul_f32_e32 v129, 0xbfb8aa3b, v131
	v_exp_f32_e32 v128, v128
	v_exp_f32_e32 v129, v129
	s_nop 0
	v_pk_add_f32 v[128:129], v[128:129], 1.0 op_sel_hi:[1,0]
	s_nop 0
	v_mov_b32_e32 v152, v129
	v_rcp_f32_e32 v153, v152
	s_nop 0
	v_fma_f32 v154, -v152, v153, 1.0
	v_fmac_f32_e32 v153, v154, v153
	v_mul_f32_e32 v155, v131, v153
	v_div_fixup_f32 v129, v155, v129, v131
	v_mov_b32_e32 v131, v128
	v_rcp_f32_e32 v152, v131
	s_nop 0
	v_fma_f32 v153, -v131, v152, 1.0
	v_fmac_f32_e32 v152, v153, v152
	v_mul_f32_e32 v154, v130, v152
	v_div_fixup_f32 v128, v154, v128, v130
	v_cvt_pk_bf16_f32 v130, v132, v133
	v_add_u32_e32 v132, v147, v141
	v_pk_mul_f32 v[128:129], v[134:135], v[128:129]
	v_ashrrev_i32_e32 v133, 31, v132
	v_pk_mul_f32 v[134:135], v[146:147], v[128:129] op_sel_hi:[0,1]
	v_lshlrev_b64 v[132:133], 10, v[132:133]
	v_cvt_pk_bf16_f32 v128, v148, v149
	v_cvt_pk_bf16_f32 v129, v150, v151
	v_cvt_pk_bf16_f32 v131, v134, v135
	v_lshl_add_u64 v[132:133], v[144:145], 0, v[132:133]
	global_store_dwordx4 v[132:133], v[128:131], off
.LBB0_744:
	s_or_b64 exec, exec, s[48:49]
	v_or_b32_e32 v147, s46, v161
	v_cmp_lt_i32_e32 vcc, v147, v140
	s_and_saveexec_b64 s[48:49], vcc
	s_cbranch_execz .LBB0_735
	s_ashr_i32 s47, s46, 31
	v_lshl_add_u64 v[128:129], s[46:47], 0, v[138:139]
	v_lshl_add_u64 v[128:129], v[128:129], 2, v[142:143]
	global_load_dword v146, v[128:129], off offset:384
	ds_read_b128 v[132:135], v166 offset:50688
	ds_read_b128 v[128:131], v166 offset:50704
	s_waitcnt lgkmcnt(1)
	v_mul_f32_e32 v148, 0xbfb8aa3b, v132
	v_mul_f32_e32 v153, 0xbfb8aa3b, v133
	v_exp_f32_e32 v152, v148
	v_exp_f32_e32 v153, v153
	ds_read_b128 v[148:151], v166 offset:50944
	v_pk_add_f32 v[152:153], v[152:153], 1.0 op_sel_hi:[1,0]
	s_nop 0
	v_mov_b32_e32 v154, v153
	v_rcp_f32_e32 v155, v154
	s_nop 0
	v_fma_f32 v167, -v154, v155, 1.0
	v_fmac_f32_e32 v155, v167, v155
	v_mul_f32_e32 v168, v133, v155
	v_div_fixup_f32 v133, v168, v153, v133
	v_mov_b32_e32 v153, v152
	v_rcp_f32_e32 v154, v153
	s_nop 0
	v_fma_f32 v155, -v153, v154, 1.0
	v_fmac_f32_e32 v154, v155, v154
	v_mul_f32_e32 v167, v132, v154
	v_div_fixup_f32 v132, v167, v152, v132
	s_waitcnt lgkmcnt(0)
	v_pk_mul_f32 v[132:133], v[148:149], v[132:133]
	s_waitcnt vmcnt(0)
	v_pk_mul_f32 v[148:149], v[146:147], v[132:133] op_sel_hi:[0,1]
	v_mul_f32_e32 v132, 0xbfb8aa3b, v134
	v_mul_f32_e32 v133, 0xbfb8aa3b, v135
	v_exp_f32_e32 v132, v132
	v_exp_f32_e32 v133, v133
	s_nop 0
	v_pk_add_f32 v[132:133], v[132:133], 1.0 op_sel_hi:[1,0]
	s_nop 0
	v_mov_b32_e32 v152, v133
	v_rcp_f32_e32 v153, v152
	s_nop 0
	v_fma_f32 v154, -v152, v153, 1.0
	v_fmac_f32_e32 v153, v154, v153
	v_mul_f32_e32 v155, v135, v153
	v_div_fixup_f32 v133, v155, v133, v135
	v_mov_b32_e32 v135, v132
	v_rcp_f32_e32 v152, v135
	s_nop 0
	v_fma_f32 v153, -v135, v152, 1.0
	v_fmac_f32_e32 v152, v153, v152
	v_mul_f32_e32 v154, v134, v152
	v_div_fixup_f32 v132, v154, v132, v134
	v_pk_mul_f32 v[132:133], v[150:151], v[132:133]
	v_mul_f32_e32 v153, 0xbfb8aa3b, v129
	v_pk_mul_f32 v[150:151], v[146:147], v[132:133] op_sel_hi:[0,1]
	v_mul_f32_e32 v132, 0xbfb8aa3b, v128
	v_exp_f32_e32 v152, v132
	v_exp_f32_e32 v153, v153
	ds_read_b128 v[132:135], v166 offset:50960
	v_pk_add_f32 v[152:153], v[152:153], 1.0 op_sel_hi:[1,0]
	s_nop 0
	v_mov_b32_e32 v154, v153
	v_rcp_f32_e32 v155, v154
	s_nop 0
	v_fma_f32 v167, -v154, v155, 1.0
	v_fmac_f32_e32 v155, v167, v155
	v_mul_f32_e32 v168, v129, v155
	v_div_fixup_f32 v129, v168, v153, v129
	v_mov_b32_e32 v153, v152
	v_rcp_f32_e32 v154, v153
	s_nop 0
	v_fma_f32 v155, -v153, v154, 1.0
	v_fmac_f32_e32 v154, v155, v154
	v_mul_f32_e32 v167, v128, v154
	v_div_fixup_f32 v128, v167, v152, v128
	s_waitcnt lgkmcnt(0)
	v_pk_mul_f32 v[128:129], v[132:133], v[128:129]
	s_nop 0
	v_pk_mul_f32 v[132:133], v[146:147], v[128:129] op_sel_hi:[0,1]
	v_mul_f32_e32 v128, 0xbfb8aa3b, v130
	v_mul_f32_e32 v129, 0xbfb8aa3b, v131
	v_exp_f32_e32 v128, v128
	v_exp_f32_e32 v129, v129
	s_nop 0
	v_pk_add_f32 v[128:129], v[128:129], 1.0 op_sel_hi:[1,0]
	s_nop 0
	v_mov_b32_e32 v152, v129
	v_rcp_f32_e32 v153, v152
	s_nop 0
	v_fma_f32 v154, -v152, v153, 1.0
	v_fmac_f32_e32 v153, v154, v153
	v_mul_f32_e32 v155, v131, v153
	v_div_fixup_f32 v129, v155, v129, v131
	v_mov_b32_e32 v131, v128
	v_rcp_f32_e32 v152, v131
	s_nop 0
	v_fma_f32 v153, -v131, v152, 1.0
	v_fmac_f32_e32 v152, v153, v152
	v_mul_f32_e32 v154, v130, v152
	v_div_fixup_f32 v128, v154, v128, v130
	v_cvt_pk_bf16_f32 v130, v132, v133
	v_add_u32_e32 v132, v147, v141
	v_pk_mul_f32 v[128:129], v[134:135], v[128:129]
	v_ashrrev_i32_e32 v133, 31, v132
	v_pk_mul_f32 v[134:135], v[146:147], v[128:129] op_sel_hi:[0,1]
	v_lshlrev_b64 v[132:133], 10, v[132:133]
	v_cvt_pk_bf16_f32 v128, v148, v149
	v_cvt_pk_bf16_f32 v129, v150, v151
	v_cvt_pk_bf16_f32 v131, v134, v135
	v_lshl_add_u64 v[132:133], v[144:145], 0, v[132:133]
	global_store_dwordx4 v[132:133], v[128:131], off
	s_branch .LBB0_735
